# GEMM K loop: per-segment s_setprio toggling replaced by one static priority raise for waves 4-7 (the younger wave of each SIMD)
# speedup vs baseline: 1.0039x; 1.0039x over previous
.LBB0_234:
	s_add_u32 s40, s40, 0x80
	s_addc_u32 s41, s41, 0
	s_add_u32 s39, s42, 0x100
	v_mov_b32_e32 v0, 0
	s_addc_u32 s78, s43, 0
	s_mov_b32 s42, 0
	v_mov_b32_e32 v1, v0
	v_mov_b32_e32 v2, v0
	v_mov_b32_e32 v3, v0
	v_mov_b32_e32 v32, v0
	v_mov_b32_e32 v33, v0
	v_mov_b32_e32 v34, v0
	v_mov_b32_e32 v35, v0
	v_mov_b32_e32 v4, v0
	v_mov_b32_e32 v5, v0
	v_mov_b32_e32 v6, v0
	v_mov_b32_e32 v7, v0
	v_mov_b32_e32 v36, v0
	v_mov_b32_e32 v37, v0
	v_mov_b32_e32 v38, v0
	v_mov_b32_e32 v39, v0
	v_mov_b32_e32 v8, v0
	v_mov_b32_e32 v9, v0
	v_mov_b32_e32 v10, v0
	v_mov_b32_e32 v11, v0
	v_mov_b32_e32 v40, v0
	v_mov_b32_e32 v41, v0
	v_mov_b32_e32 v42, v0
	v_mov_b32_e32 v43, v0
	v_mov_b32_e32 v12, v0
	v_mov_b32_e32 v13, v0
	v_mov_b32_e32 v14, v0
	v_mov_b32_e32 v15, v0
	v_mov_b32_e32 v44, v0
	v_mov_b32_e32 v45, v0
	v_mov_b32_e32 v46, v0
	v_mov_b32_e32 v47, v0
	v_mov_b32_e32 v64, v0
	v_mov_b32_e32 v65, v0
	v_mov_b32_e32 v66, v0
	v_mov_b32_e32 v67, v0
	v_mov_b32_e32 v96, v0
	v_mov_b32_e32 v97, v0
	v_mov_b32_e32 v98, v0
	v_mov_b32_e32 v99, v0
	v_mov_b32_e32 v68, v0
	v_mov_b32_e32 v69, v0
	v_mov_b32_e32 v70, v0
	v_mov_b32_e32 v71, v0
	v_mov_b32_e32 v100, v0
	v_mov_b32_e32 v101, v0
	v_mov_b32_e32 v102, v0
	v_mov_b32_e32 v103, v0
	v_mov_b32_e32 v72, v0
	v_mov_b32_e32 v73, v0
	v_mov_b32_e32 v74, v0
	v_mov_b32_e32 v75, v0
	v_mov_b32_e32 v104, v0
	v_mov_b32_e32 v105, v0
	v_mov_b32_e32 v106, v0
	v_mov_b32_e32 v107, v0
	v_mov_b32_e32 v76, v0
	v_mov_b32_e32 v77, v0
	v_mov_b32_e32 v78, v0
	v_mov_b32_e32 v79, v0
	v_mov_b32_e32 v108, v0
	v_mov_b32_e32 v109, v0
	v_mov_b32_e32 v110, v0
	v_mov_b32_e32 v111, v0
	v_mov_b32_e32 v16, v0
	v_mov_b32_e32 v17, v0
	v_mov_b32_e32 v18, v0
	v_mov_b32_e32 v19, v0
	v_mov_b32_e32 v48, v0
	v_mov_b32_e32 v49, v0
	v_mov_b32_e32 v50, v0
	v_mov_b32_e32 v51, v0
	v_mov_b32_e32 v20, v0
	v_mov_b32_e32 v21, v0
	s_waitcnt lgkmcnt(0)
	v_mov_b32_e32 v22, v0
	v_mov_b32_e32 v23, v0
	v_mov_b32_e32 v52, v0
	v_mov_b32_e32 v53, v0
	v_mov_b32_e32 v54, v0
	v_mov_b32_e32 v55, v0
	v_mov_b32_e32 v24, v0
	v_mov_b32_e32 v25, v0
	v_mov_b32_e32 v26, v0
	v_mov_b32_e32 v27, v0
	v_mov_b32_e32 v56, v0
	v_mov_b32_e32 v57, v0
	v_mov_b32_e32 v58, v0
	v_mov_b32_e32 v59, v0
	v_mov_b32_e32 v28, v0
	v_mov_b32_e32 v29, v0
	v_mov_b32_e32 v30, v0
	v_mov_b32_e32 v31, v0
	v_mov_b32_e32 v60, v0
	v_mov_b32_e32 v61, v0
	v_mov_b32_e32 v62, v0
	v_mov_b32_e32 v63, v0
	v_mov_b32_e32 v80, v0
	v_mov_b32_e32 v81, v0
	v_mov_b32_e32 v82, v0
	v_mov_b32_e32 v83, v0
	v_mov_b32_e32 v112, v0
	v_mov_b32_e32 v113, v0
	v_mov_b32_e32 v114, v0
	v_mov_b32_e32 v115, v0
	v_mov_b32_e32 v84, v0
	v_mov_b32_e32 v85, v0
	v_mov_b32_e32 v86, v0
	v_mov_b32_e32 v87, v0
	v_mov_b32_e32 v116, v0
	v_mov_b32_e32 v117, v0
	v_mov_b32_e32 v118, v0
	v_mov_b32_e32 v119, v0
	v_mov_b32_e32 v88, v0
	v_mov_b32_e32 v89, v0
	v_mov_b32_e32 v90, v0
	v_mov_b32_e32 v91, v0
	v_mov_b32_e32 v120, v0
	v_mov_b32_e32 v121, v0
	v_mov_b32_e32 v122, v0
	v_mov_b32_e32 v123, v0
	v_mov_b32_e32 v92, v0
	v_mov_b32_e32 v93, v0
	v_mov_b32_e32 v94, v0
	v_mov_b32_e32 v95, v0
	v_mov_b32_e32 v124, v0
	v_mov_b32_e32 v125, v0
	v_mov_b32_e32 v126, v0
	v_mov_b32_e32 v127, v0
	v_readfirstlane_b32 s98, v186
	s_nop 1
	s_bitcmp1_b32 s98, 8
	s_cbranch_scc0 .Lprio_lo
	s_setprio 1
	s_branch .Lprio_done
.Lprio_lo:
	s_setprio 0
.Lprio_done:
.LBB0_235:
	s_add_i32 s79, s42, 2
	s_add_u32 s82, s40, 0x80
	s_addc_u32 s43, s41, 0
	s_add_i32 s86, 0, 0x10000
	s_cmp_eq_u32 s49, s42
	s_cselect_b32 s43, s1, s43
	s_cselect_b32 s42, s0, s82
	v_add_u32_e32 v136, s86, v207
	s_cselect_b32 s83, s17, s78
	s_cselect_b32 s82, s16, s39
	s_add_i32 vcc_lo, 0, 0x14000
	ds_read_b128 v[128:131], v136
	ds_read_b128 v[132:135], v136 offset:1024
	ds_read_b128 v[150:153], v136 offset:2048
	ds_read_b128 v[154:157], v136 offset:3072
	v_add_u32_e32 v136, vcc_lo, v207
	ds_read_b128 v[158:161], v136
	ds_read_b128 v[162:165], v136 offset:1024
	ds_read_b128 v[166:169], v136 offset:2048
	ds_read_b128 v[170:173], v136 offset:3072
	v_lshl_add_u64 v[230:231], s[40:41], 0, v[144:145]
	s_add_i32 m0, s53, 0xc000
	ds_read_b128 v[174:177], v208
	ds_read_b128 v[178:181], v208 offset:1024
	ds_read_b128 v[182:185], v208 offset:2048
	ds_read_b128 v[210:213], v208 offset:3072
	ds_read_b128 v[214:217], v208 offset:4096
	ds_read_b128 v[218:221], v208 offset:5120
	ds_read_b128 v[222:225], v208 offset:6144
	ds_read_b128 v[226:229], v208 offset:7168
	global_load_lds_dwordx4 v[230:231], off
	v_lshl_add_u64 v[230:231], s[40:41], 0, v[146:147]
	s_add_i32 m0, s53, 0xe000
	s_nop 0
	global_load_lds_dwordx4 v[230:231], off
	s_waitcnt vmcnt(8)
	s_waitcnt lgkmcnt(0)
	s_barrier
	s_waitcnt lgkmcnt(0)
	v_mfma_f32_16x16x32_bf16 v[124:127], v[128:131], v[174:177], v[124:127]
	v_mfma_f32_16x16x32_bf16 v[92:95], v[150:153], v[174:177], v[92:95]
	v_mfma_f32_16x16x32_bf16 v[120:123], v[128:131], v[182:185], v[120:123]
	v_mfma_f32_16x16x32_bf16 v[88:91], v[150:153], v[182:185], v[88:91]
	v_mfma_f32_16x16x32_bf16 v[116:119], v[128:131], v[214:217], v[116:119]
	v_mfma_f32_16x16x32_bf16 v[84:87], v[150:153], v[214:217], v[84:87]
	v_mfma_f32_16x16x32_bf16 v[112:115], v[128:131], v[222:225], v[112:115]
	v_mfma_f32_16x16x32_bf16 v[80:83], v[150:153], v[222:225], v[80:83]
	v_mfma_f32_16x16x32_bf16 v[124:127], v[132:135], v[178:181], v[124:127]
	v_mfma_f32_16x16x32_bf16 v[92:95], v[154:157], v[178:181], v[92:95]
	v_mfma_f32_16x16x32_bf16 v[120:123], v[132:135], v[210:213], v[120:123]
	v_mfma_f32_16x16x32_bf16 v[88:91], v[154:157], v[210:213], v[88:91]
	v_mfma_f32_16x16x32_bf16 v[116:119], v[132:135], v[218:221], v[116:119]
	v_mfma_f32_16x16x32_bf16 v[84:87], v[154:157], v[218:221], v[84:87]
	v_mfma_f32_16x16x32_bf16 v[112:115], v[132:135], v[226:229], v[112:115]
	v_mfma_f32_16x16x32_bf16 v[80:83], v[154:157], v[226:229], v[80:83]
	v_mfma_f32_16x16x32_bf16 v[60:63], v[158:161], v[174:177], v[60:63]
	v_mfma_f32_16x16x32_bf16 v[28:31], v[166:169], v[174:177], v[28:31]
	v_mfma_f32_16x16x32_bf16 v[56:59], v[158:161], v[182:185], v[56:59]
	v_mfma_f32_16x16x32_bf16 v[24:27], v[166:169], v[182:185], v[24:27]
	v_mfma_f32_16x16x32_bf16 v[52:55], v[158:161], v[214:217], v[52:55]
	v_mfma_f32_16x16x32_bf16 v[20:23], v[166:169], v[214:217], v[20:23]
	v_mfma_f32_16x16x32_bf16 v[48:51], v[158:161], v[222:225], v[48:51]
	v_mfma_f32_16x16x32_bf16 v[16:19], v[166:169], v[222:225], v[16:19]
	v_mfma_f32_16x16x32_bf16 v[60:63], v[162:165], v[178:181], v[60:63]
	v_mfma_f32_16x16x32_bf16 v[28:31], v[170:173], v[178:181], v[28:31]
	v_mfma_f32_16x16x32_bf16 v[56:59], v[162:165], v[210:213], v[56:59]
	v_mfma_f32_16x16x32_bf16 v[24:27], v[170:173], v[210:213], v[24:27]
	v_mfma_f32_16x16x32_bf16 v[52:55], v[162:165], v[218:221], v[52:55]
	v_mfma_f32_16x16x32_bf16 v[20:23], v[170:173], v[218:221], v[20:23]
	v_mfma_f32_16x16x32_bf16 v[48:51], v[162:165], v[226:229], v[48:51]
	v_mfma_f32_16x16x32_bf16 v[16:19], v[170:173], v[226:229], v[16:19]
	s_barrier
	s_add_i32 s86, s86, s52
	v_lshl_add_u64 v[230:231], s[82:83], 0, v[138:139]
	s_mov_b32 m0, s86
	ds_read_b128 v[174:177], v208 offset:16384
	ds_read_b128 v[178:181], v208 offset:17408
	ds_read_b128 v[182:185], v208 offset:18432
	ds_read_b128 v[210:213], v208 offset:19456
	ds_read_b128 v[214:217], v208 offset:20480
	ds_read_b128 v[218:221], v208 offset:21504
	ds_read_b128 v[222:225], v208 offset:22528
	ds_read_b128 v[226:229], v208 offset:23552
	global_load_lds_dwordx4 v[230:231], off
	s_add_i32 m0, s86, 0x2000
	v_lshl_add_u64 v[232:233], s[82:83], 0, v[140:141]
	s_add_u32 s82, s82, s80
	s_addc_u32 s83, s83, 0
	s_add_i32 s86, vcc_lo, s52
	global_load_lds_dwordx4 v[232:233], off
	v_lshl_add_u64 v[234:235], s[82:83], 0, v[138:139]
	s_mov_b32 m0, s86
	v_lshl_add_u64 v[236:237], s[82:83], 0, v[140:141]
	global_load_lds_dwordx4 v[234:235], off
	s_add_i32 m0, s86, 0x2000
	v_lshl_add_u64 v[238:239], s[42:43], 0, v[138:139]
	global_load_lds_dwordx4 v[236:237], off
	s_mov_b32 m0, s53
	v_lshl_add_u64 v[240:241], s[42:43], 0, v[140:141]
	global_load_lds_dwordx4 v[238:239], off
	s_mov_b32 m0, s6
	s_nop 0
	global_load_lds_dwordx4 v[240:241], off
	s_waitcnt vmcnt(8)
	s_waitcnt lgkmcnt(0)
	s_barrier
	s_waitcnt lgkmcnt(0)
	v_mfma_f32_16x16x32_bf16 v[108:111], v[128:131], v[174:177], v[108:111]
	v_mfma_f32_16x16x32_bf16 v[76:79], v[150:153], v[174:177], v[76:79]
	v_mfma_f32_16x16x32_bf16 v[104:107], v[128:131], v[182:185], v[104:107]
	v_mfma_f32_16x16x32_bf16 v[72:75], v[150:153], v[182:185], v[72:75]
	v_mfma_f32_16x16x32_bf16 v[100:103], v[128:131], v[214:217], v[100:103]
	v_mfma_f32_16x16x32_bf16 v[68:71], v[150:153], v[214:217], v[68:71]
	v_mfma_f32_16x16x32_bf16 v[96:99], v[128:131], v[222:225], v[96:99]
	v_mfma_f32_16x16x32_bf16 v[64:67], v[150:153], v[222:225], v[64:67]
	v_mfma_f32_16x16x32_bf16 v[108:111], v[132:135], v[178:181], v[108:111]
	v_mfma_f32_16x16x32_bf16 v[76:79], v[154:157], v[178:181], v[76:79]
	v_mfma_f32_16x16x32_bf16 v[104:107], v[132:135], v[210:213], v[104:107]
	v_mfma_f32_16x16x32_bf16 v[72:75], v[154:157], v[210:213], v[72:75]
	v_mfma_f32_16x16x32_bf16 v[100:103], v[132:135], v[218:221], v[100:103]
	v_mfma_f32_16x16x32_bf16 v[68:71], v[154:157], v[218:221], v[68:71]
	v_mfma_f32_16x16x32_bf16 v[96:99], v[132:135], v[226:229], v[96:99]
	v_mfma_f32_16x16x32_bf16 v[64:67], v[154:157], v[226:229], v[64:67]
	v_mfma_f32_16x16x32_bf16 v[44:47], v[158:161], v[174:177], v[44:47]
	v_mfma_f32_16x16x32_bf16 v[12:15], v[166:169], v[174:177], v[12:15]
	v_mfma_f32_16x16x32_bf16 v[40:43], v[158:161], v[182:185], v[40:43]
	v_mfma_f32_16x16x32_bf16 v[8:11], v[166:169], v[182:185], v[8:11]
	v_mfma_f32_16x16x32_bf16 v[36:39], v[158:161], v[214:217], v[36:39]
	v_mfma_f32_16x16x32_bf16 v[4:7], v[166:169], v[214:217], v[4:7]
	v_mfma_f32_16x16x32_bf16 v[32:35], v[158:161], v[222:225], v[32:35]
	v_mfma_f32_16x16x32_bf16 v[0:3], v[166:169], v[222:225], v[0:3]
	v_mfma_f32_16x16x32_bf16 v[44:47], v[162:165], v[178:181], v[44:47]
	v_mfma_f32_16x16x32_bf16 v[12:15], v[170:173], v[178:181], v[12:15]
	v_mfma_f32_16x16x32_bf16 v[40:43], v[162:165], v[210:213], v[40:43]
	v_mfma_f32_16x16x32_bf16 v[8:11], v[170:173], v[210:213], v[8:11]
	v_mfma_f32_16x16x32_bf16 v[36:39], v[162:165], v[218:221], v[36:39]
	v_mfma_f32_16x16x32_bf16 v[4:7], v[170:173], v[218:221], v[4:7]
	v_mfma_f32_16x16x32_bf16 v[32:35], v[162:165], v[226:229], v[32:35]
	v_mfma_f32_16x16x32_bf16 v[0:3], v[170:173], v[226:229], v[0:3]
	s_barrier
	s_add_i32 s82, 0, 0x18000
	v_add_u32_e32 v136, s82, v207
	s_add_i32 s83, 0, 0x1c000
	ds_read_b128 v[128:131], v136
	ds_read_b128 v[132:135], v136 offset:1024
	ds_read_b128 v[150:153], v136 offset:2048
	ds_read_b128 v[154:157], v136 offset:3072
	v_add_u32_e32 v136, s83, v207
	ds_read_b128 v[158:161], v136
	ds_read_b128 v[162:165], v136 offset:1024
	ds_read_b128 v[166:169], v136 offset:2048
	ds_read_b128 v[170:173], v136 offset:3072
	s_add_u32 s42, s42, s80
	s_addc_u32 s43, s43, 0
	s_mov_b32 m0, s7
	v_lshl_add_u64 v[242:243], s[42:43], 0, v[138:139]
	ds_read_b128 v[174:177], v208 offset:32768
	ds_read_b128 v[178:181], v208 offset:33792
	ds_read_b128 v[182:185], v208 offset:34816
	ds_read_b128 v[210:213], v208 offset:35840
	ds_read_b128 v[214:217], v208 offset:36864
	ds_read_b128 v[218:221], v208 offset:37888
	ds_read_b128 v[222:225], v208 offset:38912
	ds_read_b128 v[226:229], v208 offset:39936
	global_load_lds_dwordx4 v[242:243], off
	v_lshl_add_u64 v[242:243], s[42:43], 0, v[140:141]
	s_mov_b32 m0, s22
	s_nop 0
	global_load_lds_dwordx4 v[242:243], off
	s_waitcnt vmcnt(8)
	s_waitcnt lgkmcnt(0)
	s_barrier
	s_waitcnt lgkmcnt(0)
	v_mfma_f32_16x16x32_bf16 v[124:127], v[128:131], v[174:177], v[124:127]
	v_mfma_f32_16x16x32_bf16 v[92:95], v[150:153], v[174:177], v[92:95]
	v_mfma_f32_16x16x32_bf16 v[120:123], v[128:131], v[182:185], v[120:123]
	v_mfma_f32_16x16x32_bf16 v[88:91], v[150:153], v[182:185], v[88:91]
	v_mfma_f32_16x16x32_bf16 v[116:119], v[128:131], v[214:217], v[116:119]
	v_mfma_f32_16x16x32_bf16 v[84:87], v[150:153], v[214:217], v[84:87]
	v_mfma_f32_16x16x32_bf16 v[112:115], v[128:131], v[222:225], v[112:115]
	v_mfma_f32_16x16x32_bf16 v[80:83], v[150:153], v[222:225], v[80:83]
	v_mfma_f32_16x16x32_bf16 v[124:127], v[132:135], v[178:181], v[124:127]
	v_mfma_f32_16x16x32_bf16 v[92:95], v[154:157], v[178:181], v[92:95]
	v_mfma_f32_16x16x32_bf16 v[120:123], v[132:135], v[210:213], v[120:123]
	v_mfma_f32_16x16x32_bf16 v[88:91], v[154:157], v[210:213], v[88:91]
	v_mfma_f32_16x16x32_bf16 v[116:119], v[132:135], v[218:221], v[116:119]
	v_mfma_f32_16x16x32_bf16 v[84:87], v[154:157], v[218:221], v[84:87]
	v_mfma_f32_16x16x32_bf16 v[112:115], v[132:135], v[226:229], v[112:115]
	v_mfma_f32_16x16x32_bf16 v[80:83], v[154:157], v[226:229], v[80:83]
	v_mfma_f32_16x16x32_bf16 v[60:63], v[158:161], v[174:177], v[60:63]
	v_mfma_f32_16x16x32_bf16 v[28:31], v[166:169], v[174:177], v[28:31]
	v_mfma_f32_16x16x32_bf16 v[56:59], v[158:161], v[182:185], v[56:59]
	v_mfma_f32_16x16x32_bf16 v[24:27], v[166:169], v[182:185], v[24:27]
	v_mfma_f32_16x16x32_bf16 v[52:55], v[158:161], v[214:217], v[52:55]
	v_mfma_f32_16x16x32_bf16 v[20:23], v[166:169], v[214:217], v[20:23]
	v_mfma_f32_16x16x32_bf16 v[48:51], v[158:161], v[222:225], v[48:51]
	v_mfma_f32_16x16x32_bf16 v[16:19], v[166:169], v[222:225], v[16:19]
	v_mfma_f32_16x16x32_bf16 v[60:63], v[162:165], v[178:181], v[60:63]
	v_mfma_f32_16x16x32_bf16 v[28:31], v[170:173], v[178:181], v[28:31]
	v_mfma_f32_16x16x32_bf16 v[56:59], v[162:165], v[210:213], v[56:59]
	v_mfma_f32_16x16x32_bf16 v[24:27], v[170:173], v[210:213], v[24:27]
	v_mfma_f32_16x16x32_bf16 v[52:55], v[162:165], v[218:221], v[52:55]
	v_mfma_f32_16x16x32_bf16 v[20:23], v[170:173], v[218:221], v[20:23]
	v_mfma_f32_16x16x32_bf16 v[48:51], v[162:165], v[226:229], v[48:51]
	v_mfma_f32_16x16x32_bf16 v[16:19], v[170:173], v[226:229], v[16:19]
	s_barrier
	s_add_i32 s42, s82, s52
	v_lshl_add_u64 v[230:231], v[230:231], 0, s[96:97]
	s_mov_b32 m0, s42
	ds_read_b128 v[174:177], v208 offset:49152
	ds_read_b128 v[178:181], v208 offset:50176
	ds_read_b128 v[182:185], v208 offset:51200
	ds_read_b128 v[210:213], v208 offset:52224
	ds_read_b128 v[214:217], v208 offset:53248
	ds_read_b128 v[218:221], v208 offset:54272
	ds_read_b128 v[222:225], v208 offset:55296
	ds_read_b128 v[226:229], v208 offset:56320
	global_load_lds_dwordx4 v[230:231], off
	v_lshl_add_u64 v[230:231], v[232:233], 0, s[96:97]
	s_add_i32 m0, s42, 0x2000
	s_add_i32 s42, s83, s52
	global_load_lds_dwordx4 v[230:231], off
	v_lshl_add_u64 v[230:231], v[234:235], 0, s[96:97]
	s_mov_b32 m0, s42
	s_nop 0
	global_load_lds_dwordx4 v[230:231], off
	v_lshl_add_u64 v[230:231], v[236:237], 0, s[96:97]
	s_add_i32 m0, s42, 0x2000
	s_nop 0
	global_load_lds_dwordx4 v[230:231], off
	v_lshl_add_u64 v[230:231], v[238:239], 0, s[96:97]
	s_mov_b32 m0, s23
	s_nop 0
	global_load_lds_dwordx4 v[230:231], off
	v_lshl_add_u64 v[230:231], v[240:241], 0, s[96:97]
	s_mov_b32 m0, s48
	s_nop 0
	global_load_lds_dwordx4 v[230:231], off
	s_waitcnt vmcnt(8)
	s_waitcnt lgkmcnt(0)
	s_barrier
	s_waitcnt lgkmcnt(0)
	v_mfma_f32_16x16x32_bf16 v[108:111], v[128:131], v[174:177], v[108:111]
	v_mfma_f32_16x16x32_bf16 v[76:79], v[150:153], v[174:177], v[76:79]
	v_mfma_f32_16x16x32_bf16 v[104:107], v[128:131], v[182:185], v[104:107]
	v_mfma_f32_16x16x32_bf16 v[72:75], v[150:153], v[182:185], v[72:75]
	v_mfma_f32_16x16x32_bf16 v[100:103], v[128:131], v[214:217], v[100:103]
	v_mfma_f32_16x16x32_bf16 v[68:71], v[150:153], v[214:217], v[68:71]
	v_mfma_f32_16x16x32_bf16 v[96:99], v[128:131], v[222:225], v[96:99]
	v_mfma_f32_16x16x32_bf16 v[64:67], v[150:153], v[222:225], v[64:67]
	v_mfma_f32_16x16x32_bf16 v[108:111], v[132:135], v[178:181], v[108:111]
	v_mfma_f32_16x16x32_bf16 v[76:79], v[154:157], v[178:181], v[76:79]
	v_mfma_f32_16x16x32_bf16 v[104:107], v[132:135], v[210:213], v[104:107]
	v_mfma_f32_16x16x32_bf16 v[72:75], v[154:157], v[210:213], v[72:75]
	v_mfma_f32_16x16x32_bf16 v[100:103], v[132:135], v[218:221], v[100:103]
	v_mfma_f32_16x16x32_bf16 v[68:71], v[154:157], v[218:221], v[68:71]
	v_mfma_f32_16x16x32_bf16 v[96:99], v[132:135], v[226:229], v[96:99]
	v_mfma_f32_16x16x32_bf16 v[64:67], v[154:157], v[226:229], v[64:67]
	v_mfma_f32_16x16x32_bf16 v[44:47], v[158:161], v[174:177], v[44:47]
	v_mfma_f32_16x16x32_bf16 v[12:15], v[166:169], v[174:177], v[12:15]
	v_mfma_f32_16x16x32_bf16 v[40:43], v[158:161], v[182:185], v[40:43]
	v_mfma_f32_16x16x32_bf16 v[8:11], v[166:169], v[182:185], v[8:11]
	v_mfma_f32_16x16x32_bf16 v[36:39], v[158:161], v[214:217], v[36:39]
	v_mfma_f32_16x16x32_bf16 v[4:7], v[166:169], v[214:217], v[4:7]
	v_mfma_f32_16x16x32_bf16 v[32:35], v[158:161], v[222:225], v[32:35]
	v_mfma_f32_16x16x32_bf16 v[0:3], v[166:169], v[222:225], v[0:3]
	v_mfma_f32_16x16x32_bf16 v[44:47], v[162:165], v[178:181], v[44:47]
	v_mfma_f32_16x16x32_bf16 v[12:15], v[170:173], v[178:181], v[12:15]
	v_mfma_f32_16x16x32_bf16 v[40:43], v[162:165], v[210:213], v[40:43]
	v_mfma_f32_16x16x32_bf16 v[8:11], v[170:173], v[210:213], v[8:11]
	v_mfma_f32_16x16x32_bf16 v[36:39], v[162:165], v[218:221], v[36:39]
	v_mfma_f32_16x16x32_bf16 v[4:7], v[170:173], v[218:221], v[4:7]
	v_mfma_f32_16x16x32_bf16 v[32:35], v[162:165], v[226:229], v[32:35]
	v_mfma_f32_16x16x32_bf16 v[0:3], v[170:173], v[226:229], v[0:3]
	s_barrier
	s_add_u32 s40, s40, 0x100
	s_addc_u32 s41, s41, 0
	s_add_u32 s39, s39, 0x100
	s_addc_u32 s78, s78, 0
	s_cmp_ge_u32 s79, s50
	s_mov_b32 s42, s79
	s_cbranch_scc0 .LBB0_235
	s_setprio 0
	s_and_b64 vcc, exec, s[88:89]
	s_cbranch_vccz .LBB0_238
	s_barrier
